# gMLP prompt item: LayerNorm partial sums of the first item requested before the preceding drain wait/barrier (one round trip less per item)
# speedup vs baseline: 1.0010x; 1.0002x over previous
; #define GIN(i) GPTR(const float, args.in[i])
; __device__ __forceinline__ void gmlp_prompt_item(LAS unsigned char* lds, int tid, int lane, int wave, size_t row0, const bf16* VG, const bf16* UG, const float* VST, ...
;     ...
;     if (tid < 128) { const f32x4* q = (const f32x4*)(VST + (row0 + tid) * 16); const f32x4 a = q[0], b = q[1], c = q[2], d = q[3];
; __global__ void __launch_bounds__(NWAVES * 64, 2) hymba_fwd(Args args) {
;     ...
;             __syncthreads();
;             for (int it = bx; it < 2 * (MP / CHUNK); it += G)
;                 gmlp_prompt_item(lds, tid, lane, wave, (size_t)(it >> 1) * CHUNK, VG, UG, VST, (const bf16*)(ws + WS_WSM) + (size_t)L * NH * CHUNK * CHUNK, (const float*)(ws + WS_WSUM) + (size_t)L * NH * CHUNK,
;                                  GIN(I_GV) + L * GMW, GIN(I_BV) + L * GMW, GIN(I_BS) + L * NH * CHUNK, YCAT, (float*)(ws + WS_GQ) + (size_t)(it & 1) * MP, (it & 1) * 2);
.LBB0_901:
	v_readlane_b32 s0, v254, 34
	v_readlane_b32 s1, v254, 35
	v_readlane_b32 s58, v254, 7
	s_and_b64 vcc, exec, s[0:1]
	v_readlane_b32 s62, v253, 47
	v_readlane_b32 s59, v254, 8
	v_readlane_b32 s57, v254, 11
	v_readlane_b32 s28, v254, 36
	s_ashr_i32 s28, s28, 1
	s_ashr_i32 s29, s28, 31
	s_lshl_b64 s[28:29], s[28:29], 7
	v_mov_b32_e32 v136, v192
	v_ashrrev_i32_e32 v137, 31, v192
	v_lshl_add_u64 v[136:137], s[28:29], 0, v[136:137]
	v_lshlrev_b64 v[136:137], 6, v[136:137]
	v_lshl_add_u64 v[136:137], s[58:59], 0, v[136:137]
	global_load_dwordx4 v[120:123], v[136:137], off
	global_load_dwordx4 v[124:127], v[136:137], off offset:16
	global_load_dwordx4 v[128:131], v[136:137], off offset:32
	global_load_dwordx4 v[132:135], v[136:137], off offset:48
	s_mov_b32 s26, 1
	s_waitcnt vmcnt(0)
	s_barrier
	v_readlane_b32 s63, v253, 48
	s_cbranch_vccnz .LBB0_747
	v_ashrrev_i32_e32 v2, 4, v192
	v_and_b32_e32 v88, -8, v2
	v_add_u32_e32 v2, 0x200, v192
	v_ashrrev_i32_e32 v2, 4, v2
	v_and_b32_e32 v90, -8, v2
	v_add_u32_e32 v2, 0x400, v192
	v_ashrrev_i32_e32 v2, 4, v2
	s_lshl_b32 s2, s56, 4
	s_movk_i32 s0, 0x80
	v_and_b32_e32 v92, -8, v2
	v_add_u32_e32 v2, 0x600, v192
	s_ashr_i32 s3, s2, 31
	v_cmp_gt_i32_e32 vcc, s0, v192
	v_ashrrev_i32_e32 v2, 4, v2
	s_lshl_b64 s[4:5], s[2:3], 1
	v_readlane_b32 s0, v254, 61
	v_and_b32_e32 v86, 0x7f, v192
	v_and_b32_e32 v94, -8, v2
	s_add_u32 s0, s0, s4
	v_readlane_b32 s1, v254, 62
	v_lshrrev_b32_e32 v2, 1, v192
	v_and_b32_e32 v84, 15, v192
	s_addc_u32 s1, s1, s5
	v_and_b32_e32 v2, 24, v2
	v_lshl_add_u32 v87, v86, 2, 0
	v_lshlrev_b32_e32 v4, 1, v86
	v_lshl_add_u64 v[96:97], s[0:1], 0, v[2:3]
	v_sub_u32_e32 v7, v87, v4
	v_or_b32_e32 v4, s2, v84
	s_movk_i32 s0, 0x110
	v_mul_lo_u32 v4, v4, s0
	v_lshl_or_b32 v14, v196, 11, v2
	v_add_u32_e32 v9, 0, v4
	v_or_b32_e32 v4, 0x38000, v14
	v_mov_b32_e32 v5, v3
	v_lshl_or_b32 v2, v84, 11, v2
	v_lshl_add_u32 v6, v196, 2, 0
	s_lshl_b32 s6, s56, 9
	v_lshl_add_u64 v[4:5], s[4:5], 0, v[4:5]
	s_mov_b64 s[8:9], 0xbc00400
	v_lshl_add_u64 v[100:101], v[2:3], 0, s[4:5]
	v_or_b32_e32 v2, 0x18000, v14
	v_and_b32_e32 v8, 48, v192
	v_mul_lo_u32 v10, v88, s0
	v_mul_lo_u32 v11, v90, s0
	v_mul_lo_u32 v12, v92, s0
	v_mul_lo_u32 v13, v94, s0
	v_lshl_add_u64 v[98:99], v[4:5], 0, s[8:9]
	v_lshl_add_u64 v[4:5], s[4:5], 0, v[2:3]
	s_lshl_b64 s[2:3], s[2:3], 2
	v_add_u32_e32 v214, s6, v6
	v_readlane_b32 s6, v255, 1
	v_ashrrev_i32_e32 v193, 31, v192
	v_lshl_add_u32 v85, v192, 2, 0
	v_ashrrev_i32_e32 v89, 31, v88
	v_ashrrev_i32_e32 v91, 31, v90
	v_ashrrev_i32_e32 v93, 31, v92
	v_ashrrev_i32_e32 v95, 31, v94
	v_lshl_or_b32 v200, v84, 8, v8
	v_cmp_gt_u32_e64 s[0:1], 16, v196
	v_lshl_add_u64 v[102:103], v[4:5], 0, s[8:9]
	v_or_b32_e32 v104, s2, v8
	v_mov_b32_e32 v105, s3
	v_add_u32_e32 v201, v7, v10
	v_add_u32_e32 v202, v7, v11
	v_add_u32_e32 v203, v7, v12
	v_add_u32_e32 v204, v7, v13
	v_add_u32_e32 v205, v9, v8
	v_readlane_b32 s7, v255, 2
	v_readlane_b32 s18, v254, 36
	s_branch .LBB0_904

; __device__ __forceinline__ void gmlp_prompt_item(LAS unsigned char* lds, int tid, int lane, int wave, size_t row0, const bf16* VG, const bf16* UG, const float* VST, ...
;     ...
;     if (tid < 128) { const f32x4* q = (const f32x4*)(VST + (row0 + tid) * 16); const f32x4 a = q[0], b = q[1], c = q[2], d = q[3];
;         const float s1 = (a[0] + a[2]) + (b[0] + b[2]) + (c[0] + c[2]) + (d[0] + d[2]), s2 = (a[1] + a[3]) + (b[1] + b[3]) + (c[1] + c[3]) + (d[1] + d[3]);
;         const float m = s1 * (1.0f / 512.0f); float var = s2 * (1.0f / 512.0f) - m * m; var = var > 0.f ? var : 0.f;
;         mu[tid] = m; rs[tid] = __builtin_amdgcn_rsqf(var + NORM_EPS); }
;     __syncthreads();
;     float sq[8];
; #pragma unroll
;     for (int i = 0; i < 8; ++i) sq[i] = 0.f;
;     v4u vq[4]; v2u uqn[8]; float biasn[8];
; #pragma unroll
;     for (int it = 0; it < 4; ++it) { const int piece = tid + 512 * it; vq[it] = *(const v4u*)(VG + (row0 + (piece & 127)) * GMW + h0 * 128 + 8 * (piece >> 7)); }
; #pragma unroll
;     for (int tb = 0; tb < 8; ++tb) { uqn[tb] = *(const v2u*)(UG + (row0 + 16 * tb + fr) * GMW + h0 * 128 + 16 * wave + 4 * fq); biasn[tb] = b_s[h0 * 128 + 16 * tb + fr]; }
.LBB0_904:
	s_ashr_i32 s12, s18, 1
	v_readlane_b32 s36, v252, 26
	s_ashr_i32 s13, s12, 31
	v_readlane_b32 s40, v252, 30
	v_readlane_b32 s41, v252, 31
	v_readlane_b32 s42, v252, 32
	v_readlane_b32 s43, v252, 33
	v_readlane_b32 s46, v252, 36
	v_readlane_b32 s47, v252, 37
	s_lshl_b64 s[8:9], s[12:13], 7
	s_mov_b64 s[2:3], s[40:41]
	s_mov_b64 s[10:11], s[42:43]
	s_mov_b64 s[14:15], s[46:47]
	v_readlane_b32 s37, v252, 27
	v_readlane_b32 s38, v252, 28
	v_readlane_b32 s39, v252, 29
	v_readlane_b32 s44, v252, 34
	v_readlane_b32 s45, v252, 35
	v_readlane_b32 s48, v252, 38
	v_readlane_b32 s49, v252, 39
	v_readlane_b32 s50, v252, 40
	v_readlane_b32 s51, v252, 41
	s_and_saveexec_b64 s[4:5], vcc
	s_cbranch_execz .LBB0_906
	s_cmp_eq_u32 s26, 0
	s_cbranch_scc1 .Lgm_ld
	v_mov_b64_e32 v[4:5], v[120:121]
	v_mov_b64_e32 v[6:7], v[122:123]
	v_mov_b64_e32 v[8:9], v[124:125]
	v_mov_b64_e32 v[10:11], v[126:127]
	v_mov_b64_e32 v[12:13], v[128:129]
	v_mov_b64_e32 v[14:15], v[130:131]
	v_mov_b64_e32 v[16:17], v[132:133]
	v_mov_b64_e32 v[18:19], v[134:135]
	s_branch .Lgm_have
.Lgm_ld:
	v_lshl_add_u64 v[4:5], s[8:9], 0, v[192:193]
	v_lshlrev_b64 v[4:5], 6, v[4:5]
	v_lshl_add_u64 v[16:17], s[58:59], 0, v[4:5]
	global_load_dwordx4 v[4:7], v[16:17], off
	global_load_dwordx4 v[8:11], v[16:17], off offset:16
	global_load_dwordx4 v[12:15], v[16:17], off offset:32
	s_nop 0
	global_load_dwordx4 v[16:19], v[16:17], off offset:48
.Lgm_have:
	s_mov_b32 s20, 0x3b000000
	s_waitcnt vmcnt(0)
	v_pk_add_f32 v[4:5], v[4:5], v[6:7]
	s_waitcnt vmcnt(2)
	v_pk_add_f32 v[6:7], v[8:9], v[10:11]
	s_waitcnt vmcnt(1)
	v_pk_add_f32 v[8:9], v[12:13], v[14:15]
	v_pk_add_f32 v[4:5], v[4:5], v[6:7]
	s_waitcnt vmcnt(0)
	v_pk_add_f32 v[6:7], v[16:17], v[18:19]
	v_pk_add_f32 v[4:5], v[4:5], v[8:9]
	s_nop 0
	v_pk_add_f32 v[4:5], v[4:5], v[6:7]
	s_nop 0
	v_pk_mul_f32 v[4:5], v[4:5], s[20:21] op_sel_hi:[1,0]
	s_nop 0
	v_fma_f32 v2, -v4, v4, v5
	v_max_f32_e32 v2, 0, v2
	v_add_f32_e32 v2, 0x358637bd, v2
	v_rsq_f32_e32 v2, v2
	ds_write2st64_b32 v85, v4, v2 offset0:136 offset1:138
.LBB0_906:
	s_or_b64 exec, exec, s[4:5]
	s_mov_b32 s26, 0
	v_cndmask_b32_e64 v36, 0, 1, s[6:7]
	v_mov_b32_e32 v5, s9
	v_readfirstlane_b32 s19, v36
	s_lshl_b32 s4, s19, 10
	s_add_u32 s4, s80, s4
	s_addc_u32 s5, s81, 0
	s_lshl_b32 s19, s19, 16
	s_add_u32 s20, s78, s19
	s_addc_u32 s21, s79, 0
	s_add_u32 s14, s14, s90
	v_or_b32_e32 v4, s8, v86
	s_addc_u32 s15, s15, s91
	s_and_b32 s19, s18, 1
	v_lshlrev_b64 v[4:5], 10, v[4:5]
	v_lshl_add_u64 v[4:5], s[64:65], 0, v[4:5]
	s_lshl_b32 s84, s19, 9
	v_lshl_add_u64 v[12:13], v[4:5], 0, s[84:85]
	v_lshl_add_u64 v[108:109], v[88:89], 1, v[12:13]
	v_lshl_add_u64 v[110:111], v[90:91], 1, v[12:13]
	v_lshl_add_u64 v[112:113], v[92:93], 1, v[12:13]
	v_lshl_add_u64 v[114:115], v[94:95], 1, v[12:13]
	v_mov_b32_e32 v13, s9
	v_or_b32_e32 v12, s8, v84
	v_lshl_add_u64 v[20:21], v[96:97], 0, s[84:85]
	v_lshlrev_b64 v[22:23], 10, v[12:13]
	v_lshlrev_b32_e32 v2, 2, v84
	v_lshl_add_u64 v[116:117], v[20:21], 0, v[22:23]
	v_lshl_or_b32 v2, s19, 10, v2
	v_or_b32_e32 v24, 0x4000, v22
	v_mov_b32_e32 v25, v23
	v_or_b32_e32 v26, 0x8000, v22
	v_mov_b32_e32 v27, v23
	v_or_b32_e32 v28, 0xc000, v22
	v_mov_b32_e32 v29, v23
	s_waitcnt lgkmcnt(0)
	s_barrier
	global_load_dwordx4 v[4:7], v[108:109], off
	global_load_dwordx4 v[8:11], v[110:111], off
	v_lshl_add_u64 v[12:13], v[20:21], 0, v[24:25]
	v_lshl_add_u64 v[14:15], v[20:21], 0, v[26:27]
	v_lshl_add_u64 v[16:17], v[20:21], 0, v[28:29]
	global_load_dwordx2 v[182:183], v[116:117], off
	global_load_dwordx2 v[184:185], v[12:13], off
	global_load_dwordx2 v[176:177], v[14:15], off
	global_load_dwordx2 v[178:179], v[16:17], off
	v_or_b32_e32 v30, 0x10000, v22
	v_mov_b32_e32 v31, v23
	v_or_b32_e32 v32, 0x14000, v22
	v_mov_b32_e32 v33, v23
	v_or_b32_e32 v34, 0x18000, v22
	v_mov_b32_e32 v35, v23
	global_load_dword v186, v2, s[14:15]
	global_load_dword v187, v2, s[14:15] offset:64
	global_load_dword v180, v2, s[14:15] offset:128
	global_load_dword v181, v2, s[14:15] offset:192
	global_load_dword v170, v2, s[14:15] offset:256
	global_load_dword v171, v2, s[14:15] offset:320
	global_load_dword v189, v2, s[14:15] offset:384
	global_load_dword v215, v2, s[14:15] offset:448
	v_or_b32_e32 v22, 0x1c000, v22
	v_lshl_add_u64 v[12:13], v[20:21], 0, v[30:31]
	v_lshl_add_u64 v[14:15], v[20:21], 0, v[32:33]
	v_lshl_add_u64 v[16:17], v[20:21], 0, v[34:35]
	v_lshl_add_u64 v[18:19], v[20:21], 0, v[22:23]
	global_load_dwordx2 v[172:173], v[12:13], off
	global_load_dwordx2 v[174:175], v[14:15], off
	global_load_dwordx2 v[168:169], v[16:17], off
	global_load_dwordx2 v[166:167], v[18:19], off
	s_nop 0
	global_load_dwordx4 v[12:15], v[112:113], off
	global_load_dwordx4 v[16:19], v[114:115], off
	v_lshlrev_b32_e32 v36, 9, v36
	v_lshl_add_u64 v[20:21], v[20:21], 0, s[94:95]
	s_lshl_b64 s[12:13], s[12:13], 18
	v_lshl_add_u64 v[126:127], v[20:21], 0, v[24:25]
	v_lshl_add_u64 v[128:129], v[20:21], 0, v[26:27]
	v_lshl_add_u64 v[130:131], v[20:21], 0, v[28:29]
	v_lshl_add_u64 v[132:133], v[20:21], 0, v[30:31]
	v_lshl_add_u64 v[134:135], v[20:21], 0, v[32:33]
	v_lshl_add_u64 v[136:137], v[20:21], 0, v[34:35]
	v_lshl_add_u64 v[138:139], v[20:21], 0, v[22:23]
	v_or_b32_e32 v20, s12, v36
	v_mov_b32_e32 v21, s13
	v_mov_b32_e32 v122, 0
	s_mov_b32 s24, 2
	v_lshl_add_u64 v[124:125], s[14:15], 0, v[2:3]
	v_lshl_add_u64 v[140:141], v[20:21], 0, v[98:99]
	v_lshl_add_u64 v[142:143], v[20:21], 0, v[100:101]
	v_lshl_add_u64 v[144:145], v[20:21], 0, v[102:103]
	v_lshl_add_u64 v[146:147], s[2:3], 0, v[104:105]
	v_lshl_add_u64 v[148:149], s[10:11], 0, v[104:105]
	v_mov_b32_e32 v123, v122
	v_mov_b32_e32 v120, v122
	v_mov_b32_e32 v121, v122
	v_mov_b32_e32 v118, v122
	v_mov_b32_e32 v119, v122
	v_mov_b32_e32 v106, v122
	v_mov_b32_e32 v107, v122
	s_waitcnt vmcnt(17)
	v_mov_b64_e32 v[150:151], v[182:183]
	s_waitcnt vmcnt(16)
	v_mov_b64_e32 v[152:153], v[184:185]
	s_waitcnt vmcnt(15)
	v_mov_b64_e32 v[154:155], v[176:177]
	s_waitcnt vmcnt(14)
	v_mov_b64_e32 v[156:157], v[178:179]
	s_waitcnt vmcnt(7)
	v_mov_b32_e32 v216, v189
	s_waitcnt vmcnt(6)
	v_mov_b32_e32 v217, v215
	s_waitcnt vmcnt(5)
	v_mov_b64_e32 v[158:159], v[172:173]
	s_waitcnt vmcnt(4)
	v_mov_b64_e32 v[160:161], v[174:175]
	s_waitcnt vmcnt(3)
	v_mov_b64_e32 v[162:163], v[168:169]
	s_waitcnt vmcnt(2)
	v_mov_b64_e32 v[164:165], v[166:167]
	s_branch .LBB0_908
